# prep phase: discretised SSM input matrix loop batched (vector loads, one wait, vector stores)
# speedup vs baseline: 1.0083x; 1.0057x over previous
; DI void prep_item(const CP& p, int item, char* smem) {
;     ...
;     const float dt = expf(p.log_dt[l * 16 + g]);
;     const float lr = p.lam_re[l * 1024 + gp], li = p.lam_im[l * 1024 + gp];
;     const float mag = expf(lr * dt);
;     const double ang = (double)li * (double)dt;
;     const float are = mag * (float)cos(ang), aim = mag * (float)sin(ang);
;     const float magL = expf(lr * dt * 64.f);
;     const float aLr = magL * (float)cos(ang * 64.0), aLi = magL * (float)sin(ang * 64.0);
.LBB0_28:
	s_or_b64 exec, exec, s[4:5]
	s_waitcnt vmcnt(0)
	v_mul_f32_e32 v5, v5, v6
	v_mul_f32_e32 v28, 0x42800000, v5
	v_mul_f32_e32 v29, 0x3fb8aa3b, v28
	v_fma_f32 v30, v28, s33, -v29
	v_rndne_f32_e32 v31, v29
	v_fmac_f32_e32 v30, 0x32a5705f, v28
	v_sub_f32_e32 v29, v29, v31
	v_add_f32_e32 v29, v29, v30
	v_cvt_i32_f32_e32 v30, v31
	v_exp_f32_e32 v29, v29
	v_cmp_ngt_f32_e32 vcc, s82, v28
	v_mov_b64_e32 v[42:43], s[48:49]
	v_mul_f64 v[48:49], v[24:25], 0.5
	v_ldexp_f32 v29, v29, v30
	v_cndmask_b32_e32 v29, 0, v29, vcc
	v_cmp_nlt_f32_e32 vcc, s84, v28
	s_mov_b32 s70, s58
	v_cmp_ngt_f32_e64 s[4:5], s82, v5
	v_cndmask_b32_e32 v35, v1, v29, vcc
	v_mul_f64 v[28:29], v[20:21], v[20:21]
	v_mul_f64 v[30:31], v[28:29], 0.5
	v_fma_f64 v[46:47], s[50:51], v[28:29], v[42:43]
	v_add_f64 v[32:33], -v[30:31], 1.0
	v_fma_f64 v[46:47], v[28:29], v[46:47], s[52:53]
	v_add_f64 v[38:39], -v[32:33], 1.0
	v_fma_f64 v[46:47], v[28:29], v[46:47], s[54:55]
	v_add_f64 v[30:31], v[38:39], -v[30:31]
	v_fma_f64 v[46:47], v[28:29], v[46:47], s[56:57]
	v_mul_f64 v[38:39], v[28:29], v[28:29]
	v_fma_f64 v[46:47], v[28:29], v[46:47], s[58:59]
	v_fma_f64 v[30:31], v[20:21], -v[24:25], v[30:31]
	v_fmac_f64_e32 v[30:31], v[38:39], v[46:47]
	v_add_f64 v[30:31], v[32:33], v[30:31]
	v_mov_b64_e32 v[32:33], s[60:61]
	v_fma_f64 v[38:39], s[62:63], v[28:29], v[32:33]
	v_fma_f64 v[38:39], v[28:29], v[38:39], s[64:65]
	v_fma_f64 v[38:39], v[28:29], v[38:39], s[66:67]
	v_fma_f64 v[38:39], v[28:29], v[38:39], s[68:69]
	v_mul_f64 v[46:47], v[20:21], -v[28:29]
	v_fmac_f64_e32 v[48:49], v[46:47], v[38:39]
	v_fma_f64 v[24:25], v[28:29], v[48:49], -v[24:25]
	v_fmac_f64_e32 v[24:25], s[70:71], v[46:47]
	v_add_f64 v[20:21], v[20:21], -v[24:25]
	v_and_b32_e32 v24, 1, v40
	v_xor_b32_e32 v21, 0x80000000, v21
	v_cmp_eq_u32_e32 vcc, 0, v24
	v_lshlrev_b32_e32 v24, 30, v40
	s_nop 0
	v_cndmask_b32_e32 v20, v20, v30, vcc
	v_cndmask_b32_e32 v21, v21, v31, vcc
	v_cmp_class_f64_e64 vcc, v[14:15], s87
	v_mul_f32_e32 v14, 0x3fb8aa3b, v5
	v_bitop3_b32 v21, v21, v24, s86 bitop3:0x78
	v_fma_f32 v24, v5, s33, -v14
	v_rndne_f32_e32 v25, v14
	v_fmac_f32_e32 v24, 0x32a5705f, v5
	v_sub_f32_e32 v14, v14, v25
	v_add_f32_e32 v14, v14, v24
	v_exp_f32_e32 v14, v14
	v_cvt_i32_f32_e32 v24, v25
	v_cndmask_b32_e32 v20, 0, v20, vcc
	v_cndmask_b32_e32 v21, v67, v21, vcc
	v_cvt_f32_f64_e32 v20, v[20:21]
	v_ldexp_f32 v14, v14, v24
	v_mul_f64 v[24:25], v[16:17], v[16:17]
	v_mul_f64 v[28:29], v[24:25], 0.5
	v_fma_f64 v[46:47], s[50:51], v[24:25], v[42:43]
	v_add_f64 v[30:31], -v[28:29], 1.0
	v_fma_f64 v[46:47], v[24:25], v[46:47], s[52:53]
	v_add_f64 v[38:39], -v[30:31], 1.0
	v_fma_f64 v[46:47], v[24:25], v[46:47], s[54:55]
	v_add_f64 v[28:29], v[38:39], -v[28:29]
	v_fma_f64 v[46:47], v[24:25], v[46:47], s[56:57]
	v_mul_f64 v[38:39], v[24:25], v[24:25]
	v_fma_f64 v[46:47], v[24:25], v[46:47], s[58:59]
	v_fma_f64 v[28:29], v[16:17], -v[18:19], v[28:29]
	v_fmac_f64_e32 v[28:29], v[38:39], v[46:47]
	v_add_f64 v[28:29], v[30:31], v[28:29]
	v_fma_f64 v[30:31], s[62:63], v[24:25], v[32:33]
	v_fma_f64 v[30:31], v[24:25], v[30:31], s[64:65]
	v_fma_f64 v[30:31], v[24:25], v[30:31], s[66:67]
	v_fma_f64 v[30:31], v[24:25], v[30:31], s[68:69]
	v_mul_f64 v[38:39], v[16:17], -v[24:25]
	v_mul_f64 v[46:47], v[18:19], 0.5
	v_fmac_f64_e32 v[46:47], v[38:39], v[30:31]
	v_cndmask_b32_e64 v14, 0, v14, s[4:5]
	v_cmp_nlt_f32_e64 s[4:5], s84, v5
	v_fma_f64 v[18:19], v[24:25], v[46:47], -v[18:19]
	v_fmac_f64_e32 v[18:19], s[70:71], v[38:39]
	v_cndmask_b32_e64 v5, v1, v14, s[4:5]
	v_and_b32_e32 v14, 1, v37
	v_add_f64 v[16:17], v[16:17], -v[18:19]
	v_cmp_eq_u32_e64 s[4:5], 0, v14
	v_mul_f32_e32 v20, v35, v20
	s_nop 0
	v_cndmask_b32_e64 v14, v28, v16, s[4:5]
	v_cndmask_b32_e64 v16, v29, v17, s[4:5]
	v_lshlrev_b32_e32 v17, 30, v37
	v_xor_b32_e32 v17, v17, v9
	v_bitop3_b32 v16, v16, v17, s86 bitop3:0x78
	v_cmp_class_f64_e64 s[4:5], v[8:9], s87
	s_nop 1
	v_cndmask_b32_e64 v8, 0, v14, s[4:5]
	v_cndmask_b32_e64 v9, v67, v16, s[4:5]
	v_cvt_f32_f64_e32 v8, v[8:9]
	v_mul_f32_e32 v19, v5, v8
	v_mul_f64 v[8:9], v[10:11], v[10:11]
	v_mul_f64 v[16:17], v[8:9], 0.5
	v_fma_f64 v[30:31], s[50:51], v[8:9], v[42:43]
	v_add_f64 v[24:25], -v[16:17], 1.0
	v_fma_f64 v[30:31], v[8:9], v[30:31], s[52:53]
	v_add_f64 v[28:29], -v[24:25], 1.0
	v_fma_f64 v[30:31], v[8:9], v[30:31], s[54:55]
	v_add_f64 v[16:17], v[28:29], -v[16:17]
	v_fma_f64 v[30:31], v[8:9], v[30:31], s[56:57]
	v_mul_f64 v[28:29], v[8:9], v[8:9]
	v_fma_f64 v[30:31], v[8:9], v[30:31], s[58:59]
	v_fma_f64 v[16:17], v[10:11], -v[12:13], v[16:17]
	v_fmac_f64_e32 v[16:17], v[28:29], v[30:31]
	v_add_f64 v[16:17], v[24:25], v[16:17]
	v_fma_f64 v[24:25], s[62:63], v[8:9], v[32:33]
	v_fma_f64 v[24:25], v[8:9], v[24:25], s[64:65]
	v_fma_f64 v[24:25], v[8:9], v[24:25], s[66:67]
	v_fma_f64 v[24:25], v[8:9], v[24:25], s[68:69]
	v_mul_f64 v[28:29], v[10:11], -v[8:9]
	v_mul_f64 v[30:31], v[12:13], 0.5
	v_fmac_f64_e32 v[30:31], v[28:29], v[24:25]
	v_fma_f64 v[8:9], v[8:9], v[30:31], -v[12:13]
	v_fmac_f64_e32 v[8:9], s[70:71], v[28:29]
	v_add_f64 v[8:9], v[10:11], -v[8:9]
	v_and_b32_e32 v10, 1, v3
	v_xor_b32_e32 v9, 0x80000000, v9
	v_cmp_eq_u32_e64 s[6:7], 0, v10
	v_lshlrev_b32_e32 v3, 30, v3
	s_nop 0
	v_cndmask_b32_e64 v9, v9, v17, s[6:7]
	v_cndmask_b32_e64 v8, v8, v16, s[6:7]
	v_bitop3_b32 v3, v9, v3, s86 bitop3:0x78
	v_cndmask_b32_e64 v8, 0, v8, s[4:5]
	v_cndmask_b32_e64 v9, v67, v3, s[4:5]
	v_cvt_f32_f64_e32 v28, v[8:9]
	v_mul_f64 v[8:9], v[22:23], v[22:23]
	v_mul_f64 v[10:11], v[8:9], 0.5
	v_fmac_f64_e32 v[42:43], s[50:51], v[8:9]
	v_add_f64 v[12:13], -v[10:11], 1.0
	v_fma_f64 v[24:25], v[8:9], v[42:43], s[52:53]
	v_add_f64 v[16:17], -v[12:13], 1.0
	v_fma_f64 v[24:25], v[8:9], v[24:25], s[54:55]
	v_add_f64 v[10:11], v[16:17], -v[10:11]
	v_fma_f64 v[24:25], v[8:9], v[24:25], s[56:57]
	v_mul_f64 v[16:17], v[8:9], v[8:9]
	v_fma_f64 v[24:25], v[8:9], v[24:25], s[58:59]
	v_fma_f64 v[10:11], v[22:23], -v[26:27], v[10:11]
	v_fmac_f64_e32 v[10:11], v[16:17], v[24:25]
	v_fmac_f64_e32 v[32:33], s[62:63], v[8:9]
	v_add_f64 v[10:11], v[12:13], v[10:11]
	v_fma_f64 v[12:13], v[8:9], v[32:33], s[64:65]
	v_fma_f64 v[12:13], v[8:9], v[12:13], s[66:67]
	v_fma_f64 v[12:13], v[8:9], v[12:13], s[68:69]
	v_mul_f64 v[16:17], v[22:23], -v[8:9]
	v_mul_f64 v[24:25], v[26:27], 0.5
	v_fmac_f64_e32 v[24:25], v[16:17], v[12:13]
	v_fma_f64 v[8:9], v[8:9], v[24:25], -v[26:27]
	v_fmac_f64_e32 v[8:9], s[70:71], v[16:17]
	v_and_b32_e32 v3, 1, v41
	v_add_f64 v[8:9], v[22:23], -v[8:9]
	v_cmp_eq_u32_e64 s[4:5], 0, v3
	v_mul_f32_e32 v18, v5, v28
	s_nop 0
	v_cndmask_b32_e64 v3, v10, v8, s[4:5]
	v_cndmask_b32_e64 v8, v11, v9, s[4:5]
	v_lshlrev_b32_e32 v9, 30, v41
	s_load_dwordx2 s[10:11], s[0:1], 0x140
	s_load_dwordx4 s[4:7], s[0:1], 0x130
	v_xor_b32_e32 v9, v9, v15
	v_bitop3_b32 v9, v8, v9, s86 bitop3:0x78
	v_cndmask_b32_e32 v8, 0, v3, vcc
	v_cndmask_b32_e32 v9, v67, v9, vcc
	v_cvt_f32_f64_e32 v3, v[8:9]
	v_mul_f32_e32 v21, v35, v3
	s_waitcnt lgkmcnt(0)
; DI void prep_item(const CP& p, int item, char* smem) {
;     ...
;     *(fl4*)(p.ssmc + ((size_t)l * 1024 + gp) * 4) = mk_f4(are, aim, aLr, aLi);
;     const float den = lr * lr + li * li;
;     const float nr = are - 1.f, ni = aim;
;     const float cre = (nr * lr + ni * li) / den, cim = (ni * lr - nr * li) / den;
;     const float* br = p.b_re + ((size_t)l * 1024 + gp) * 16;
;     const float* bi = p.b_im + ((size_t)l * 1024 + gp) * 16;
;     float* bbp = p.ssmbb + ((size_t)l * 1024 + gp) * 32;
; #pragma unroll
;     for (int h = 0; h < 16; ++h) {
;       bbp[2 * h] = cre * br[h] - cim * bi[h];
;       bbp[2 * h + 1] = cre * bi[h] + cim * br[h];
;     }
	v_mov_b32_e32 v8, s4
	v_mov_b32_e32 v9, s5
	s_lshl_b64 s[4:5], s[20:21], 10
	v_ashrrev_i32_e32 v3, 31, v2
	v_lshl_add_u64 v[14:15], s[4:5], 0, v[2:3]
	v_lshl_add_u64 v[8:9], v[14:15], 4, v[8:9]
	global_store_dwordx4 v[8:9], v[18:21], off
	s_load_dwordx8 s[12:19], s[0:1], 0x68
	v_lshlrev_b64 v[8:9], 6, v[14:15]
	v_fma_f32 v18, v5, v28, -1.0
	v_pk_mul_f32 v[16:17], v[6:7], v[18:19]
	s_waitcnt lgkmcnt(0)
	v_lshl_add_u64 v[12:13], s[14:15], 0, v[8:9]
	v_lshl_add_u64 v[10:11], s[12:13], 0, v[8:9]
	global_load_dword v20, v[12:13], off
	global_load_dword v21, v[10:11], off
	v_mov_b32_e32 v8, v19
	v_mov_b32_e32 v9, v6
	v_pk_mul_f32 v[8:9], v[6:7], v[8:9] op_sel_hi:[0,1]
	v_mov_b32_e32 v6, v7
	v_mov_b32_e32 v19, v7
	v_pk_mul_f32 v[6:7], v[6:7], v[18:19] op_sel_hi:[0,1]
	v_add_f32_e32 v5, v16, v17
	v_add_f32_e32 v7, v9, v7
	v_div_scale_f32 v9, s[4:5], v7, v7, v5
	v_rcp_f32_e32 v16, v9
	v_sub_f32_e32 v8, v8, v6
	v_fma_f32 v17, -v9, v16, 1.0
	v_fmac_f32_e32 v16, v17, v16
	v_div_scale_f32 v17, vcc, v5, v7, v5
	v_mul_f32_e32 v18, v17, v16
	v_fma_f32 v19, -v9, v18, v17
	v_fmac_f32_e32 v18, v19, v16
	v_fma_f32 v9, -v9, v18, v17
	v_div_scale_f32 v17, s[4:5], v7, v7, v8
	v_rcp_f32_e32 v19, v17
	v_div_fmas_f32 v6, v9, v16, v18
	v_div_fixup_f32 v6, v6, v7, v5
	s_lshl_b64 s[4:5], s[20:21], 14
	v_fma_f32 v5, -v17, v19, 1.0
	v_fmac_f32_e32 v19, v5, v19
	v_div_scale_f32 v5, vcc, v8, v7, v8
	v_mul_f32_e32 v9, v5, v19
	v_fma_f32 v16, -v17, v9, v5
	v_fmac_f32_e32 v9, v16, v19
	v_fma_f32 v5, -v17, v9, v5
	v_div_fmas_f32 v5, v5, v19, v9
	v_div_fixup_f32 v8, v5, v7, v8
	v_lshlrev_b64 v[16:17], 7, v[14:15]
	v_lshl_add_u64 v[16:17], s[6:7], 0, v[16:17]
	v_mov_b32_e32 v19, v34
	global_load_dwordx4 v[70:73], v[10:11], off
	global_load_dwordx4 v[74:77], v[10:11], off offset:16
	global_load_dwordx4 v[78:81], v[10:11], off offset:32
	global_load_dwordx4 v[82:85], v[10:11], off offset:48
	global_load_dwordx4 v[86:89], v[12:13], off
	global_load_dwordx4 v[90:93], v[12:13], off offset:16
	global_load_dwordx4 v[94:97], v[12:13], off offset:32
	global_load_dwordx4 v[98:101], v[12:13], off offset:48
	s_waitcnt vmcnt(0)
	v_mul_f32_e32 v102, v8, v86
	v_mul_f32_e32 v103, v8, v70
	v_fma_f32 v102, v6, v70, -v102
	v_fmac_f32_e32 v103, v6, v86
	v_mul_f32_e32 v104, v8, v87
	v_mul_f32_e32 v105, v8, v71
	v_fma_f32 v104, v6, v71, -v104
	v_fmac_f32_e32 v105, v6, v87
	v_mul_f32_e32 v106, v8, v88
	v_mul_f32_e32 v107, v8, v72
	v_fma_f32 v106, v6, v72, -v106
	v_fmac_f32_e32 v107, v6, v88
	v_mul_f32_e32 v108, v8, v89
	v_mul_f32_e32 v109, v8, v73
	v_fma_f32 v108, v6, v73, -v108
	v_fmac_f32_e32 v109, v6, v89
	v_mul_f32_e32 v110, v8, v90
	v_mul_f32_e32 v111, v8, v74
	v_fma_f32 v110, v6, v74, -v110
	v_fmac_f32_e32 v111, v6, v90
	v_mul_f32_e32 v112, v8, v91
	v_mul_f32_e32 v113, v8, v75
	v_fma_f32 v112, v6, v75, -v112
	v_fmac_f32_e32 v113, v6, v91
	v_mul_f32_e32 v114, v8, v92
	v_mul_f32_e32 v115, v8, v76
	v_fma_f32 v114, v6, v76, -v114
	v_fmac_f32_e32 v115, v6, v92
	v_mul_f32_e32 v116, v8, v93
	v_mul_f32_e32 v117, v8, v77
	v_fma_f32 v116, v6, v77, -v116
	v_fmac_f32_e32 v117, v6, v93
	v_mul_f32_e32 v118, v8, v94
	v_mul_f32_e32 v119, v8, v78
	v_fma_f32 v118, v6, v78, -v118
	v_fmac_f32_e32 v119, v6, v94
	v_mul_f32_e32 v120, v8, v95
	v_mul_f32_e32 v121, v8, v79
	v_fma_f32 v120, v6, v79, -v120
	v_fmac_f32_e32 v121, v6, v95
	v_mul_f32_e32 v122, v8, v96
	v_mul_f32_e32 v123, v8, v80
	v_fma_f32 v122, v6, v80, -v122
	v_fmac_f32_e32 v123, v6, v96
	v_mul_f32_e32 v124, v8, v97
	v_mul_f32_e32 v125, v8, v81
	v_fma_f32 v124, v6, v81, -v124
	v_fmac_f32_e32 v125, v6, v97
	v_mul_f32_e32 v126, v8, v98
	v_mul_f32_e32 v127, v8, v82
	v_fma_f32 v126, v6, v82, -v126
	v_fmac_f32_e32 v127, v6, v98
	v_mul_f32_e32 v128, v8, v99
	v_mul_f32_e32 v129, v8, v83
	v_fma_f32 v128, v6, v83, -v128
	v_fmac_f32_e32 v129, v6, v99
	v_mul_f32_e32 v130, v8, v100
	v_mul_f32_e32 v131, v8, v84
	v_fma_f32 v130, v6, v84, -v130
	v_fmac_f32_e32 v131, v6, v100
	v_mul_f32_e32 v132, v8, v101
	v_mul_f32_e32 v133, v8, v85
	v_fma_f32 v132, v6, v85, -v132
	v_fmac_f32_e32 v133, v6, v101
	global_store_dwordx4 v[16:17], v[102:105], off
	global_store_dwordx4 v[16:17], v[106:109], off offset:16
	global_store_dwordx4 v[16:17], v[110:113], off offset:32
	global_store_dwordx4 v[16:17], v[114:117], off offset:48
	global_store_dwordx4 v[16:17], v[118:121], off offset:64
	global_store_dwordx4 v[16:17], v[122:125], off offset:80
	global_store_dwordx4 v[16:17], v[126:129], off offset:96
	global_store_dwordx4 v[16:17], v[130:133], off offset:112
	global_load_dword v9, v[10:11], off offset:60
	global_load_dword v35, v[12:13], off offset:60
	s_load_dwordx2 s[6:7], s[0:1], 0x30
	v_and_b32_e32 v7, 63, v36
	v_ashrrev_i32_e32 v5, 31, v4
	v_lshl_add_u64 v[4:5], s[20:21], 4, v[4:5]
	v_lshlrev_b32_e32 v18, 1, v7
	v_lshlrev_b64 v[42:43], 12, v[4:5]
	v_lshl_add_u64 v[92:93], s[10:11], 0, v[18:19]
	s_load_dwordx2 s[10:11], s[0:1], 0x180
	s_waitcnt lgkmcnt(0)
	v_mov_b64_e32 v[4:5], s[6:7]
	v_mad_u64_u32 v[4:5], s[6:7], v14, s89, v[4:5]
	v_add_co_u32_e32 v94, vcc, s90, v4
	v_mad_i32_i24 v5, v15, s89, v5
	s_nop 0
	v_addc_co_u32_e32 v95, vcc, 0, v5, vcc
	s_load_dwordx2 s[6:7], s[0:1], 0x100
	v_lshlrev_b32_e32 v37, 2, v7
	v_or_b32_e32 v50, 0x100, v42
	v_or_b32_e32 v52, 0x200, v42
	v_or_b32_e32 v54, 0x300, v42
	v_or_b32_e32 v56, 0x400, v42
	v_or_b32_e32 v58, 0x500, v42
	v_or_b32_e32 v60, 0x600, v42
	v_or_b32_e32 v62, 0x700, v42
	v_or_b32_e32 v64, 0x800, v42
	v_or_b32_e32 v70, 0x900, v42
	v_or_b32_e32 v72, 0xa00, v42
	v_or_b32_e32 v74, 0xb00, v42
	v_or_b32_e32 v78, 0xc00, v42
	v_or_b32_e32 v82, 0xd00, v42
	v_or_b32_e32 v86, 0xe00, v42
	v_or_b32_e32 v90, 0xf00, v42
	s_waitcnt lgkmcnt(0)
; DI unsigned pk2(float a, float b) { f2_t v = {a, b}; bf2_t r = __builtin_convertvector(v, bf2_t); return __builtin_bit_cast(unsigned, r); }
; DI void prep_item(const CP& p, int item, char* smem) {
;     ...
;     {
;       u16* bm = p.bbmat + (((size_t)l * 16 + g) * 128) * 16;
; #pragma unroll
;       for (int h = 0; h < 16; ++h) {
;         bm[(size_t)pp * 16 + h] = (u16)(pk2(cre * br[h] - cim * bi[h], 0.f) & 0xffffu);
;         bm[(size_t)(64 + pp) * 16 + h] = (u16)(pk2(cre * bi[h] + cim * br[h], 0.f) & 0xffffu);
;       }
;     }
;     for (int h = 0; h < 16; ++h) {
;       const float vr = p.c_re[(((size_t)l * 16 + g) * 16 + h) * 64 + pp];
;       const float vi = p.c_im[(((size_t)l * 16 + g) * 16 + h) * 64 + pp];
;       u16* cm = p.cmat + (((size_t)l * 16 + g) * 16 + h) * 128;
;       cm[pp] = (u16)(pk2(vr, 0.f) & 0xffffu);
;       cm[64 + pp] = (u16)(pk2(-vi, 0.f) & 0xffffu);
;     }
;     const int k = q * 512 + tid;
; #pragma unroll
;     for (int j = 0; j < 4; ++j) p.wf[(size_t)l * 4096 + j * 1024 + k] = p.w_in[((size_t)l * 1024 + k) * 2308 + 2048 + j];
	s_add_u32 s4, s6, s4
	v_or_b32_e32 v20, v42, v37
	v_mov_b32_e32 v21, v43
	v_mov_b32_e32 v23, v43
	v_mov_b32_e32 v25, v43
	v_mov_b32_e32 v27, v43
	v_mov_b32_e32 v29, v43
	v_mov_b32_e32 v31, v43
	v_mov_b32_e32 v33, v43
	v_mov_b32_e32 v39, v43
	v_mov_b32_e32 v41, v43
	v_mov_b32_e32 v47, v43
	v_mov_b32_e32 v49, v43
	v_mov_b32_e32 v77, v43
	v_mov_b32_e32 v81, v43
	v_mov_b32_e32 v85, v43
	v_mov_b32_e32 v89, v43
	v_or_b32_e32 v22, v50, v37
	v_or_b32_e32 v24, v52, v37
	v_or_b32_e32 v26, v54, v37
	v_or_b32_e32 v28, v56, v37
	v_or_b32_e32 v30, v58, v37
	v_or_b32_e32 v32, v60, v37
	v_or_b32_e32 v38, v62, v37
	v_or_b32_e32 v40, v64, v37
	v_or_b32_e32 v46, v70, v37
	v_or_b32_e32 v48, v72, v37
	v_or_b32_e32 v76, v74, v37
	v_or_b32_e32 v80, v78, v37
	v_or_b32_e32 v84, v82, v37
	v_or_b32_e32 v88, v86, v37
	v_lshl_add_u64 v[96:97], s[10:11], 0, v[42:43]
	s_addc_u32 s5, s7, s5
	v_lshl_add_u64 v[14:15], s[16:17], 0, v[20:21]
	v_lshl_add_u64 v[18:19], s[16:17], 0, v[22:23]
	v_lshl_add_u64 v[98:99], s[16:17], 0, v[26:27]
	v_lshl_add_u64 v[26:27], s[18:19], 0, v[26:27]
	v_lshl_add_u64 v[100:101], s[16:17], 0, v[28:29]
	v_lshl_add_u64 v[28:29], s[18:19], 0, v[28:29]
	v_lshl_add_u64 v[102:103], s[16:17], 0, v[30:31]
	v_lshl_add_u64 v[30:31], s[18:19], 0, v[30:31]
	v_lshl_add_u64 v[104:105], s[16:17], 0, v[32:33]
	v_lshl_add_u64 v[32:33], s[18:19], 0, v[32:33]
	v_lshl_add_u64 v[106:107], s[16:17], 0, v[38:39]
	v_lshl_add_u64 v[38:39], s[18:19], 0, v[38:39]
	s_waitcnt vmcnt(1)
	v_mul_f32_e32 v4, v8, v9
	s_waitcnt vmcnt(0)
	v_fmac_f32_e32 v4, v6, v35
	global_store_dword v[16:17], v4, off offset:124
	global_load_dword v9, v[94:95], off
	v_lshl_add_u64 v[4:5], v[92:93], 0, v[42:43]
	v_or_b32_e32 v42, v90, v37
	v_lshl_add_u64 v[16:17], s[18:19], 0, v[20:21]
	v_lshl_add_u64 v[20:21], s[18:19], 0, v[22:23]
	v_lshl_add_u64 v[22:23], s[16:17], 0, v[24:25]
	v_lshl_add_u64 v[24:25], s[18:19], 0, v[24:25]
	v_lshl_add_u64 v[108:109], s[16:17], 0, v[40:41]
	v_lshl_add_u64 v[40:41], s[18:19], 0, v[40:41]
	v_lshl_add_u64 v[110:111], s[16:17], 0, v[46:47]
	v_lshl_add_u64 v[46:47], s[18:19], 0, v[46:47]
	v_lshl_add_u64 v[112:113], s[16:17], 0, v[48:49]
	v_lshl_add_u64 v[48:49], s[18:19], 0, v[48:49]
	v_lshl_add_u64 v[114:115], s[16:17], 0, v[76:77]
	v_lshl_add_u64 v[116:117], s[16:17], 0, v[80:81]
	v_lshl_add_u64 v[118:119], s[16:17], 0, v[84:85]
	v_lshl_add_u64 v[120:121], s[16:17], 0, v[88:89]
	v_lshl_add_u64 v[122:123], s[16:17], 0, v[42:43]
	v_lshl_add_u64 v[2:3], v[2:3], 2, s[4:5]
	v_lshl_add_u64 v[76:77], s[18:19], 0, v[76:77]
	v_lshl_add_u64 v[80:81], s[18:19], 0, v[80:81]
	v_lshl_add_u64 v[84:85], s[18:19], 0, v[84:85]
	v_lshl_add_u64 v[88:89], s[18:19], 0, v[88:89]
	v_lshl_add_u64 v[124:125], s[18:19], 0, v[42:43]
	global_load_dword v35, v[14:15], off
	global_load_dword v37, v[16:17], off
	global_load_dword v44, v[18:19], off
	global_load_dword v69, v[20:21], off
	global_load_dword v126, v[22:23], off
	global_load_dword v127, v[24:25], off
	s_nop 0
	global_load_dwordx4 v[14:17], v[12:13], off offset:48
	global_load_dwordx4 v[18:21], v[12:13], off offset:32
	global_load_dword v128, v[98:99], off
	global_load_dword v129, v[26:27], off
	global_load_dword v130, v[100:101], off
	global_load_dword v131, v[28:29], off
	global_load_dword v132, v[102:103], off
	global_load_dword v133, v[30:31], off
	global_load_dwordx4 v[22:25], v[12:13], off offset:16
	s_nop 0
	global_load_dwordx4 v[26:29], v[12:13], off
	s_nop 0
	global_load_dword v104, v[104:105], off
	s_nop 0
	global_load_dword v105, v[32:33], off
	s_nop 0
	global_load_dword v106, v[106:107], off
	s_nop 0
	global_load_dword v107, v[38:39], off
	s_nop 0
	global_load_dword v108, v[108:109], off
	s_nop 0
	global_load_dword v109, v[40:41], off
	s_nop 0
	global_load_dword v110, v[110:111], off
	s_nop 0
	global_load_dword v111, v[46:47], off
	global_load_dwordx4 v[30:33], v[10:11], off offset:48
	global_load_dwordx4 v[38:41], v[10:11], off offset:32
	s_nop 0
	global_load_dword v112, v[112:113], off
	s_nop 0
	global_load_dword v113, v[48:49], off
	s_nop 0
	global_load_dword v114, v[114:115], off
	s_nop 0
	global_load_dword v115, v[76:77], off
	s_nop 0
	global_load_dword v116, v[116:117], off
	s_nop 0
	global_load_dword v117, v[80:81], off
	global_load_dwordx4 v[46:49], v[10:11], off offset:16
	s_nop 0
	global_load_dwordx4 v[10:13], v[10:11], off
	s_nop 0
	global_load_dword v118, v[118:119], off
	s_nop 0
	global_load_dword v119, v[84:85], off
	s_nop 0
	global_load_dword v120, v[120:121], off
	s_nop 0
	global_load_dword v121, v[88:89], off
	s_nop 0
	global_load_dword v122, v[122:123], off
	s_nop 0
	global_load_dword v123, v[124:125], off
	v_add_co_u32_e32 v80, vcc, 0x1000, v2
	v_mov_b32_e32 v51, v43
	s_nop 0
	v_addc_co_u32_e32 v81, vcc, 0, v3, vcc
	v_add_co_u32_e32 v84, vcc, 0x2000, v2
	v_mov_b32_e32 v53, v43
	s_nop 0
	v_addc_co_u32_e32 v85, vcc, 0, v3, vcc
	v_mov_b32_e32 v55, v43
	v_mov_b32_e32 v57, v43
	v_mov_b32_e32 v59, v43
	v_mov_b32_e32 v61, v43
	v_mov_b32_e32 v63, v43
	v_mov_b32_e32 v65, v43
	v_mov_b32_e32 v71, v43
	v_mov_b32_e32 v73, v43
	v_mov_b32_e32 v75, v43
	v_mov_b32_e32 v79, v43
	v_mov_b32_e32 v83, v43
	v_mov_b32_e32 v87, v43
	v_mov_b32_e32 v91, v43
	v_mov_b32_e32 v77, v34
	v_lshlrev_b32_e32 v76, 5, v7
	v_lshl_add_u64 v[42:43], v[92:93], 0, v[50:51]
	v_lshl_add_u64 v[50:51], v[92:93], 0, v[52:53]
	v_lshl_add_u64 v[52:53], v[92:93], 0, v[54:55]
	v_lshl_add_u64 v[54:55], v[92:93], 0, v[56:57]
	v_lshl_add_u64 v[56:57], v[92:93], 0, v[58:59]
	v_lshl_add_u64 v[58:59], v[92:93], 0, v[60:61]
	v_lshl_add_u64 v[60:61], v[92:93], 0, v[62:63]
	v_lshl_add_u64 v[62:63], v[92:93], 0, v[64:65]
	v_lshl_add_u64 v[64:65], v[92:93], 0, v[70:71]
	v_lshl_add_u64 v[70:71], v[92:93], 0, v[72:73]
	v_lshl_add_u64 v[72:73], v[92:93], 0, v[74:75]
	v_lshl_add_u64 v[74:75], v[92:93], 0, v[78:79]
	v_lshl_add_u64 v[78:79], v[92:93], 0, v[82:83]
	v_lshl_add_u64 v[82:83], v[92:93], 0, v[90:91]
	v_lshl_add_u64 v[76:77], v[96:97], 0, v[76:77]
	s_waitcnt vmcnt(39)
; DI unsigned pk2(float a, float b) { f2_t v = {a, b}; bf2_t r = __builtin_convertvector(v, bf2_t); return __builtin_bit_cast(unsigned, r); }
; DI void prep_item(const CP& p, int item, char* smem) {
;     ...
;     {
;       u16* bm = p.bbmat + (((size_t)l * 16 + g) * 128) * 16;
; #pragma unroll
;       for (int h = 0; h < 16; ++h) {
;         bm[(size_t)pp * 16 + h] = (u16)(pk2(cre * br[h] - cim * bi[h], 0.f) & 0xffffu);
;         bm[(size_t)(64 + pp) * 16 + h] = (u16)(pk2(cre * bi[h] + cim * br[h], 0.f) & 0xffffu);
;       }
;     }
;     for (int h = 0; h < 16; ++h) {
;       const float vr = p.c_re[(((size_t)l * 16 + g) * 16 + h) * 64 + pp];
;       const float vi = p.c_im[(((size_t)l * 16 + g) * 16 + h) * 64 + pp];
;       u16* cm = p.cmat + (((size_t)l * 16 + g) * 16 + h) * 128;
;       cm[pp] = (u16)(pk2(vr, 0.f) & 0xffffu);
;       cm[64 + pp] = (u16)(pk2(-vi, 0.f) & 0xffffu);
;     }
;     const int k = q * 512 + tid;
; #pragma unroll
;     for (int j = 0; j < 4; ++j) p.wf[(size_t)l * 4096 + j * 1024 + k] = p.w_in[((size_t)l * 1024 + k) * 2308 + 2048 + j];
	v_cvt_pk_bf16_f32 v35, v35, s0
	s_waitcnt vmcnt(38)
	v_cvt_pk_bf16_f32 v37, -v37, s0
	s_waitcnt vmcnt(37)
	v_cvt_pk_bf16_f32 v44, v44, s0
	s_waitcnt vmcnt(36)
	v_cvt_pk_bf16_f32 v69, -v69, s0
	s_waitcnt vmcnt(35)
	v_cvt_pk_bf16_f32 v124, v126, s0
	s_waitcnt vmcnt(34)
	v_cvt_pk_bf16_f32 v125, -v127, s0
	s_mov_b64 s[4:5], 0
	s_waitcnt vmcnt(31)
	v_cvt_pk_bf16_f32 v126, v128, s0
	s_waitcnt vmcnt(30)
	v_cvt_pk_bf16_f32 v127, -v129, s0
	s_waitcnt vmcnt(29)
	v_cvt_pk_bf16_f32 v128, v130, s0
	s_waitcnt vmcnt(28)
	v_cvt_pk_bf16_f32 v129, -v131, s0
	s_waitcnt vmcnt(27)
	v_cvt_pk_bf16_f32 v130, v132, s0
	s_waitcnt vmcnt(26)
	v_cvt_pk_bf16_f32 v131, -v133, s0
	global_store_dword v[2:3], v9, off
	global_load_dword v9, v[94:95], off offset:4
	v_add_co_u32_e32 v2, vcc, 0x3000, v2
	s_waitcnt vmcnt(25)
	v_cvt_pk_bf16_f32 v104, v104, s0
	v_addc_co_u32_e32 v3, vcc, 0, v3, vcc
	s_waitcnt vmcnt(24)
	v_cvt_pk_bf16_f32 v105, -v105, s0
	s_waitcnt vmcnt(23)
	v_cvt_pk_bf16_f32 v106, v106, s0
	s_waitcnt vmcnt(22)
	v_cvt_pk_bf16_f32 v107, -v107, s0
	s_waitcnt vmcnt(21)
	v_cvt_pk_bf16_f32 v108, v108, s0
	s_waitcnt vmcnt(20)
	v_cvt_pk_bf16_f32 v109, -v109, s0
	s_waitcnt vmcnt(19)
	v_cvt_pk_bf16_f32 v110, v110, s0
	s_waitcnt vmcnt(18)
	v_cvt_pk_bf16_f32 v111, -v111, s0
	s_waitcnt vmcnt(15)
	v_cvt_pk_bf16_f32 v112, v112, s0
	s_waitcnt vmcnt(0)
	global_store_dword v[80:81], v9, off
	global_load_dword v9, v[94:95], off offset:8
	v_lshl_add_u64 v[80:81], v[92:93], 0, v[86:87]
	s_waitcnt vmcnt(0)
	global_store_dword v[84:85], v9, off
	global_load_dword v94, v[94:95], off offset:12
	v_pk_mul_f32 v[86:87], v[8:9], v[28:29] op_sel_hi:[0,1]
	v_pk_mul_f32 v[88:89], v[8:9], v[26:27] op_sel_hi:[0,1]
	v_pk_mul_f32 v[28:29], v[6:7], v[28:29] op_sel_hi:[0,1]
	v_pk_mul_f32 v[26:27], v[6:7], v[26:27] op_sel_hi:[0,1]
	v_pk_mul_f32 v[90:91], v[8:9], v[24:25] op_sel_hi:[0,1]
	v_pk_mul_f32 v[92:93], v[8:9], v[22:23] op_sel_hi:[0,1]
	v_pk_mul_f32 v[24:25], v[6:7], v[24:25] op_sel_hi:[0,1]
	v_pk_mul_f32 v[22:23], v[6:7], v[22:23] op_sel_hi:[0,1]
	v_pk_mul_f32 v[96:97], v[8:9], v[20:21] op_sel_hi:[0,1]
	v_pk_mul_f32 v[98:99], v[8:9], v[18:19] op_sel_hi:[0,1]
	v_pk_mul_f32 v[20:21], v[6:7], v[20:21] op_sel_hi:[0,1]
	v_pk_mul_f32 v[18:19], v[6:7], v[18:19] op_sel_hi:[0,1]
	v_pk_mul_f32 v[100:101], v[8:9], v[16:17] op_sel_hi:[0,1]
	v_pk_mul_f32 v[102:103], v[8:9], v[14:15] op_sel_hi:[0,1]
	v_pk_mul_f32 v[16:17], v[6:7], v[16:17] op_sel_hi:[0,1]
	v_pk_mul_f32 v[14:15], v[6:7], v[14:15] op_sel_hi:[0,1]
	v_pk_fma_f32 v[84:85], v[6:7], v[10:11], v[88:89] op_sel_hi:[0,1,1] neg_lo:[0,0,1] neg_hi:[0,0,1]
	v_pk_fma_f32 v[86:87], v[6:7], v[12:13], v[86:87] op_sel_hi:[0,1,1] neg_lo:[0,0,1] neg_hi:[0,0,1]
	v_pk_fma_f32 v[10:11], v[8:9], v[10:11], v[26:27] op_sel_hi:[0,1,1]
	v_pk_fma_f32 v[26:27], v[8:9], v[12:13], v[28:29] op_sel_hi:[0,1,1]
	v_pk_fma_f32 v[12:13], v[6:7], v[46:47], v[92:93] op_sel_hi:[0,1,1] neg_lo:[0,0,1] neg_hi:[0,0,1]
	v_pk_fma_f32 v[28:29], v[6:7], v[48:49], v[90:91] op_sel_hi:[0,1,1] neg_lo:[0,0,1] neg_hi:[0,0,1]
	v_pk_fma_f32 v[22:23], v[8:9], v[46:47], v[22:23] op_sel_hi:[0,1,1]
	v_pk_fma_f32 v[24:25], v[8:9], v[48:49], v[24:25] op_sel_hi:[0,1,1]
	v_pk_fma_f32 v[46:47], v[6:7], v[38:39], v[98:99] op_sel_hi:[0,1,1] neg_lo:[0,0,1] neg_hi:[0,0,1]
	v_pk_fma_f32 v[48:49], v[6:7], v[40:41], v[96:97] op_sel_hi:[0,1,1] neg_lo:[0,0,1] neg_hi:[0,0,1]
	v_pk_fma_f32 v[18:19], v[8:9], v[38:39], v[18:19] op_sel_hi:[0,1,1]
	v_pk_fma_f32 v[38:39], v[8:9], v[40:41], v[20:21] op_sel_hi:[0,1,1]
	v_pk_fma_f32 v[20:21], v[6:7], v[30:31], v[102:103] op_sel_hi:[0,1,1] neg_lo:[0,0,1] neg_hi:[0,0,1]
	v_pk_fma_f32 v[40:41], v[6:7], v[32:33], v[100:101] op_sel_hi:[0,1,1] neg_lo:[0,0,1] neg_hi:[0,0,1]
	v_pk_fma_f32 v[30:31], v[8:9], v[30:31], v[14:15] op_sel_hi:[0,1,1]
	v_pk_fma_f32 v[32:33], v[8:9], v[32:33], v[16:17] op_sel_hi:[0,1,1]
	v_cvt_pk_bf16_f32 v8, v12, v13
	v_cvt_pk_bf16_f32 v6, v84, v85
	v_cvt_pk_bf16_f32 v9, v28, v29
	v_cvt_pk_bf16_f32 v7, v86, v87
	v_cvt_pk_bf16_f32 v95, -v113, s0
	v_cvt_pk_bf16_f32 v113, v114, s0
	v_cvt_pk_bf16_f32 v114, -v115, s0
	v_cvt_pk_bf16_f32 v115, v116, s0
	v_cvt_pk_bf16_f32 v116, -v117, s0
	v_cvt_pk_bf16_f32 v117, v118, s0
	v_cvt_pk_bf16_f32 v118, -v119, s0
	v_cvt_pk_bf16_f32 v119, v120, s0
	v_cvt_pk_bf16_f32 v120, -v121, s0
	v_cvt_pk_bf16_f32 v121, v122, s0
	v_cvt_pk_bf16_f32 v122, -v123, s0
	v_cvt_pk_bf16_f32 v12, v22, v23
	v_cvt_pk_bf16_f32 v10, v10, v11
	v_cvt_pk_bf16_f32 v13, v24, v25
	v_cvt_pk_bf16_f32 v11, v26, v27
	v_cvt_pk_bf16_f32 v16, v20, v21
	v_cvt_pk_bf16_f32 v14, v46, v47
	v_cvt_pk_bf16_f32 v17, v40, v41
	v_cvt_pk_bf16_f32 v15, v48, v49
	v_cvt_pk_bf16_f32 v20, v30, v31
	v_cvt_pk_bf16_f32 v18, v18, v19
	v_cvt_pk_bf16_f32 v21, v32, v33
	v_cvt_pk_bf16_f32 v19, v38, v39
	global_store_dwordx4 v[76:77], v[6:9], off
	global_store_dwordx4 v[76:77], v[10:13], off offset:2048
	global_store_dwordx4 v[76:77], v[14:17], off offset:16
	global_store_dwordx4 v[76:77], v[18:21], off offset:2064
	global_store_short v[4:5], v35, off
	global_store_short v[4:5], v37, off offset:128
	global_store_short v[42:43], v44, off
	global_store_short v[42:43], v69, off offset:128
	global_store_short v[50:51], v124, off
	global_store_short v[50:51], v125, off offset:128
	global_store_short v[52:53], v126, off
	global_store_short v[52:53], v127, off offset:128
	global_store_short v[54:55], v128, off
	global_store_short v[54:55], v129, off offset:128
	global_store_short v[56:57], v130, off
	global_store_short v[56:57], v131, off offset:128
	global_store_short v[58:59], v104, off
	global_store_short v[58:59], v105, off offset:128
	global_store_short v[60:61], v106, off
	global_store_short v[60:61], v107, off offset:128
	global_store_short v[62:63], v108, off
	global_store_short v[62:63], v109, off offset:128
	global_store_short v[64:65], v110, off
	global_store_short v[64:65], v111, off offset:128
	global_store_short v[70:71], v112, off
	global_store_short v[70:71], v95, off offset:128
	global_store_short v[72:73], v113, off
	global_store_short v[72:73], v114, off offset:128
	global_store_short v[74:75], v115, off
	global_store_short v[74:75], v116, off offset:128
	global_store_short v[78:79], v117, off
	global_store_short v[78:79], v118, off offset:128
	global_store_short v[80:81], v119, off
	global_store_short v[80:81], v120, off offset:128
	global_store_short v[82:83], v121, off
	global_store_short v[82:83], v122, off offset:128
	s_waitcnt vmcnt(36)
	global_store_dword v[2:3], v94, off
